# x3 stores of the last residual GEMM phase (and its fix-up) without the nt hint so the final rmsnorm pass can hit in the memory-side cache
# speedup vs baseline: 1.0149x; 1.0069x over previous
; __device__ __forceinline__ unsigned pk2(float lo, float hi) { unsigned r; asm volatile("v_cvt_pk_bf16_f32 %0, %1, %2" : "=v"(r) : "v"(lo), "v"(hi)); return r; }
; __device__ __forceinline__ float dot4(f32x4 v) { return (v[0] * v[0] + v[1] * v[1]) + (v[2] * v[2] + v[3] * v[3]); }
;     __device__ __forceinline__ void operator()(const f32x4 (&acc)[2][2][4][2], const Unit& u, int wr, int wc, int fr, int fq) const {
;     ...
;             for (int m = 0; m < 4; ++m)
; #pragma unroll
;                 for (int bj = 0; bj < 2; ++bj) { const size_t off = (size_t)(row0 + ai * HALF + m * 16) * D + col0 + bj * HALF;
;                     if (quad >= 0 && (quad & 1) != bj) { rr[m][bj][0] = (f32x4){0.f, 0.f, 0.f, 0.f}; rr[m][bj][1] = rr[m][bj][0]; }
;                     else { rr[m][bj][0] = *(const f32x4*)(bb + off); rr[m][bj][1] = *(const f32x4*)(bb + off + 4); } }
;             __builtin_amdgcn_sched_barrier(0);
; #pragma unroll
;             for (int m = 0; m < 4; ++m) {
;                 const int row = row0 + ai * HALF + m * 16; const size_t off = (size_t)row * D + col0;
;                 float q = 0.f;
; #pragma unroll
;                 for (int bj = 0; bj < 2; ++bj) {
;                     if (quad >= 0 && (quad & 1) != bj) continue;
;                     const f32x4 v0 = rr[m][bj][0] + acc[ai][bj][m][0] * scale, v1 = rr[m][bj][1] + acc[ai][bj][m][1] * scale;
;                     q += dot4(v0) + dot4(v1);
;                     __builtin_nontemporal_store(v0, (f32x4*)(out + off + bj * HALF)); __builtin_nontemporal_store(v1, (f32x4*)(out + off + bj * HALF + 4));
;                     if (An) { const f32x4 a0 = v0 * gv[bj][0], a1 = v1 * gv[bj][1]; u32x4 w; w.x = pk2(a0[0], a0[1]); w.y = pk2(a0[2], a0[3]); w.z = pk2(a1[0], a1[1]); w.w = pk2(a1[2], a1[3]);
;                         *(u32x4*)(An + off + bj * HALF) = w; }
;                 }
;                 q += __shfl_xor(q, 16); q += __shfl_xor(q, 32);
;                 if (fq == 0) __hip_atomic_fetch_add(ss + row, q, __ATOMIC_RELAXED, __HIP_MEMORY_SCOPE_AGENT);
.LBB0_1293:
	v_lshl_or_b32 v188, s82, 8, v177
	v_ashrrev_i32_e32 v189, 31, v188
	v_lshl_add_u32 v192, s81, 8, v206
	v_lshlrev_b64 v[232:233], 2, v[188:189]
	v_ashrrev_i32_e32 v193, 31, v192
	v_or_b32_e32 v202, 16, v192
	v_lshl_add_u64 v[190:191], s[12:13], 0, v[232:233]
	v_lshlrev_b64 v[234:235], 13, v[192:193]
	v_ashrrev_i32_e32 v203, 31, v202
	v_or_b32_e32 v198, 32, v192
	v_or_b32_e32 v194, 48, v192
	v_lshl_add_u64 v[128:129], v[190:191], 0, v[234:235]
	v_lshlrev_b64 v[204:205], 13, v[202:203]
	v_ashrrev_i32_e32 v199, 31, v198
	v_ashrrev_i32_e32 v195, 31, v194
	global_load_dwordx4 v[210:213], v[128:129], off offset:16
	global_load_dwordx4 v[214:217], v[128:129], off
	global_load_dwordx4 v[218:221], v[128:129], off offset:528
	global_load_dwordx4 v[224:227], v[128:129], off offset:512
	v_lshl_add_u64 v[128:129], v[190:191], 0, v[204:205]
	v_lshlrev_b64 v[200:201], 13, v[198:199]
	v_lshlrev_b64 v[196:197], 13, v[194:195]
	global_load_dwordx4 v[168:171], v[128:129], off offset:16
	global_load_dwordx4 v[172:175], v[128:129], off
	global_load_dwordx4 v[160:163], v[128:129], off offset:528
	global_load_dwordx4 v[164:167], v[128:129], off offset:512
	v_lshl_add_u64 v[128:129], v[190:191], 0, v[200:201]
	v_lshl_add_u64 v[132:133], v[190:191], 0, v[196:197]
	global_load_dwordx4 v[152:155], v[128:129], off offset:16
	global_load_dwordx4 v[156:159], v[128:129], off
	global_load_dwordx4 v[144:147], v[128:129], off offset:528
	global_load_dwordx4 v[148:151], v[128:129], off offset:512
	global_load_dwordx4 v[136:139], v[132:133], off offset:16
	global_load_dwordx4 v[140:143], v[132:133], off
	s_nop 0
	global_load_dwordx4 v[128:131], v[132:133], off offset:528
	s_nop 0
	global_load_dwordx4 v[132:135], v[132:133], off offset:512
	s_waitcnt vmcnt(0)
	v_pk_fma_f32 v[216:217], v[126:127], 0.5, v[216:217] op_sel_hi:[1,0,1]
	v_pk_fma_f32 v[214:215], v[124:125], 0.5, v[214:215] op_sel_hi:[1,0,1]
	v_pk_fma_f32 v[228:229], v[120:121], 0.5, v[210:211] op_sel_hi:[1,0,1]
	v_mul_f32_e32 v209, v215, v215
	v_mul_f32_e32 v210, v217, v217
	v_pk_fma_f32 v[230:231], v[122:123], 0.5, v[212:213] op_sel_hi:[1,0,1]
	v_fmac_f32_e32 v209, v214, v214
	v_fmac_f32_e32 v210, v216, v216
	v_add_f32_e32 v209, v209, v210
	v_mul_f32_e32 v210, v229, v229
	v_mul_f32_e32 v211, v231, v231
	v_fmac_f32_e32 v210, v228, v228
	v_fmac_f32_e32 v211, v230, v230
	v_add_f32_e32 v210, v210, v211
	v_pk_fma_f32 v[226:227], v[94:95], 0.5, v[226:227] op_sel_hi:[1,0,1]
	v_pk_fma_f32 v[224:225], v[92:93], 0.5, v[224:225] op_sel_hi:[1,0,1]
	v_add_f32_e32 v209, v209, v210
	v_mul_f32_e32 v210, v225, v225
	v_mul_f32_e32 v211, v227, v227
	v_pk_fma_f32 v[220:221], v[90:91], 0.5, v[220:221] op_sel_hi:[1,0,1]
	v_pk_fma_f32 v[218:219], v[88:89], 0.5, v[218:219] op_sel_hi:[1,0,1]
	v_fmac_f32_e32 v210, v224, v224
	v_fmac_f32_e32 v211, v226, v226
	v_add_f32_e32 v210, v210, v211
	v_mul_f32_e32 v211, v219, v219
	v_mul_f32_e32 v212, v221, v221
	v_fmac_f32_e32 v211, v218, v218
	v_fmac_f32_e32 v212, v220, v220
	v_add_f32_e32 v211, v211, v212
	v_add_f32_e32 v210, v210, v211
	v_add_f32_e32 v212, v209, v210
	v_and_b32_e32 v210, 64, v208
	v_xor_b32_e32 v209, 16, v208
	v_add_u32_e32 v213, 64, v210
	v_cmp_lt_i32_e32 vcc, v209, v213
	v_lshl_add_u64 v[210:211], s[12:13], 0, v[234:235]
	v_lshl_add_u64 v[232:233], v[210:211], 0, v[232:233]
	v_cndmask_b32_e32 v209, v208, v209, vcc
	v_lshlrev_b32_e32 v209, 2, v209
	ds_bpermute_b32 v223, v209, v212
	v_xor_b32_e32 v210, 32, v208
	v_cmp_lt_i32_e32 vcc, v210, v213
	global_store_dwordx4 v[232:233], v[214:217], off
	global_store_dwordx4 v[232:233], v[228:231], off offset:16
	global_store_dwordx4 v[232:233], v[224:227], off offset:512
	global_store_dwordx4 v[232:233], v[218:221], off offset:528
	v_cndmask_b32_e32 v210, v208, v210, vcc
	s_waitcnt lgkmcnt(0)
	v_add_f32_e32 v211, v212, v223
	v_lshlrev_b32_e32 v210, 2, v210
	ds_bpermute_b32 v212, v210, v211
	s_and_saveexec_b64 s[48:49], s[4:5]
	s_cbranch_execz .LBB0_1295
	s_waitcnt lgkmcnt(0)
	v_add_f32_e32 v211, v211, v212
	v_lshl_add_u64 v[212:213], v[192:193], 2, s[40:41]
	global_atomic_add_f32 v[212:213], v211, off
.LBB0_1295:
	s_or_b64 exec, exec, s[48:49]
	v_pk_fma_f32 v[174:175], v[118:119], 0.5, v[174:175] op_sel_hi:[1,0,1]
	v_pk_fma_f32 v[172:173], v[116:117], 0.5, v[172:173] op_sel_hi:[1,0,1]
	v_mul_f32_e32 v211, v175, v175
	v_mul_f32_e32 v193, v173, v173
	v_pk_fma_f32 v[170:171], v[114:115], 0.5, v[170:171] op_sel_hi:[1,0,1]
	v_pk_fma_f32 v[168:169], v[112:113], 0.5, v[168:169] op_sel_hi:[1,0,1]
	v_fmac_f32_e32 v193, v172, v172
	v_fmac_f32_e32 v211, v174, v174
	v_add_f32_e32 v193, v193, v211
	v_mul_f32_e32 v211, v169, v169
	s_waitcnt lgkmcnt(0)
	v_mul_f32_e32 v212, v171, v171
	v_fmac_f32_e32 v211, v168, v168
	v_fmac_f32_e32 v212, v170, v170
	v_pk_fma_f32 v[166:167], v[86:87], 0.5, v[166:167] op_sel_hi:[1,0,1]
	v_pk_fma_f32 v[164:165], v[84:85], 0.5, v[164:165] op_sel_hi:[1,0,1]
	v_add_f32_e32 v211, v211, v212
	v_pk_fma_f32 v[212:213], v[80:81], 0.5, v[160:161] op_sel_hi:[1,0,1]
	v_mul_f32_e32 v160, v165, v165
	v_mul_f32_e32 v161, v167, v167
	v_pk_fma_f32 v[214:215], v[82:83], 0.5, v[162:163] op_sel_hi:[1,0,1]
	v_fmac_f32_e32 v160, v164, v164
	v_fmac_f32_e32 v161, v166, v166
	v_add_f32_e32 v160, v160, v161
	v_mul_f32_e32 v161, v213, v213
	v_mul_f32_e32 v162, v215, v215
	v_fmac_f32_e32 v161, v212, v212
	v_fmac_f32_e32 v162, v214, v214
	v_add_f32_e32 v161, v161, v162
	v_add_f32_e32 v193, v193, v211
	v_add_f32_e32 v160, v160, v161
	v_add_f32_e32 v193, v193, v160
	ds_bpermute_b32 v211, v209, v193
	v_lshl_add_u64 v[160:161], s[12:13], 0, v[204:205]
	v_lshl_add_u64 v[162:163], v[188:189], 2, v[160:161]
	global_store_dwordx4 v[162:163], v[172:175], off
	global_store_dwordx4 v[162:163], v[168:171], off offset:16
	global_store_dwordx4 v[162:163], v[164:167], off offset:512
	global_store_dwordx4 v[162:163], v[212:215], off offset:528
	s_waitcnt lgkmcnt(0)
	v_add_f32_e32 v160, v193, v211
	ds_bpermute_b32 v161, v210, v160
	s_and_saveexec_b64 s[48:49], s[4:5]
	s_cbranch_execz .LBB0_1297
	s_waitcnt lgkmcnt(0)
	v_add_f32_e32 v162, v160, v161
	v_lshl_add_u64 v[160:161], v[202:203], 2, s[40:41]
	global_atomic_add_f32 v[160:161], v162, off
; __device__ __forceinline__ unsigned pk2(float lo, float hi) { unsigned r; asm volatile("v_cvt_pk_bf16_f32 %0, %1, %2" : "=v"(r) : "v"(lo), "v"(hi)); return r; }
; __device__ __forceinline__ float dot4(f32x4 v) { return (v[0] * v[0] + v[1] * v[1]) + (v[2] * v[2] + v[3] * v[3]); }
;     __device__ __forceinline__ void operator()(const f32x4 (&acc)[2][2][4][2], const Unit& u, int wr, int wc, int fr, int fq) const {
;     ...
;             for (int m = 0; m < 4; ++m)
; #pragma unroll
;                 for (int bj = 0; bj < 2; ++bj) { const size_t off = (size_t)(row0 + ai * HALF + m * 16) * D + col0 + bj * HALF;
;                     if (quad >= 0 && (quad & 1) != bj) { rr[m][bj][0] = (f32x4){0.f, 0.f, 0.f, 0.f}; rr[m][bj][1] = rr[m][bj][0]; }
;                     else { rr[m][bj][0] = *(const f32x4*)(bb + off); rr[m][bj][1] = *(const f32x4*)(bb + off + 4); } }
;             __builtin_amdgcn_sched_barrier(0);
; #pragma unroll
;             for (int m = 0; m < 4; ++m) {
;                 const int row = row0 + ai * HALF + m * 16; const size_t off = (size_t)row * D + col0;
;                 float q = 0.f;
; #pragma unroll
;                 for (int bj = 0; bj < 2; ++bj) {
;                     if (quad >= 0 && (quad & 1) != bj) continue;
;                     const f32x4 v0 = rr[m][bj][0] + acc[ai][bj][m][0] * scale, v1 = rr[m][bj][1] + acc[ai][bj][m][1] * scale;
;                     q += dot4(v0) + dot4(v1);
;                     __builtin_nontemporal_store(v0, (f32x4*)(out + off + bj * HALF)); __builtin_nontemporal_store(v1, (f32x4*)(out + off + bj * HALF + 4));
;                     if (An) { const f32x4 a0 = v0 * gv[bj][0], a1 = v1 * gv[bj][1]; u32x4 w; w.x = pk2(a0[0], a0[1]); w.y = pk2(a0[2], a0[3]); w.z = pk2(a1[0], a1[1]); w.w = pk2(a1[2], a1[3]);
;                         *(u32x4*)(An + off + bj * HALF) = w; }
;                 }
;                 q += __shfl_xor(q, 16); q += __shfl_xor(q, 32);
;                 if (fq == 0) __hip_atomic_fetch_add(ss + row, q, __ATOMIC_RELAXED, __HIP_MEMORY_SCOPE_AGENT);
.LBB0_1297:
	s_or_b64 exec, exec, s[48:49]
	v_pk_fma_f32 v[158:159], v[110:111], 0.5, v[158:159] op_sel_hi:[1,0,1]
	v_pk_fma_f32 v[156:157], v[108:109], 0.5, v[156:157] op_sel_hi:[1,0,1]
	s_waitcnt lgkmcnt(0)
	v_mul_f32_e32 v161, v159, v159
	v_mul_f32_e32 v160, v157, v157
	v_pk_fma_f32 v[154:155], v[106:107], 0.5, v[154:155] op_sel_hi:[1,0,1]
	v_pk_fma_f32 v[152:153], v[104:105], 0.5, v[152:153] op_sel_hi:[1,0,1]
	v_fmac_f32_e32 v160, v156, v156
	v_fmac_f32_e32 v161, v158, v158
	v_add_f32_e32 v160, v160, v161
	v_mul_f32_e32 v161, v153, v153
	v_mul_f32_e32 v162, v155, v155
	v_fmac_f32_e32 v161, v152, v152
	v_fmac_f32_e32 v162, v154, v154
	v_add_f32_e32 v161, v161, v162
	v_pk_fma_f32 v[150:151], v[78:79], 0.5, v[150:151] op_sel_hi:[1,0,1]
	v_pk_fma_f32 v[148:149], v[76:77], 0.5, v[148:149] op_sel_hi:[1,0,1]
	v_add_f32_e32 v164, v160, v161
	v_pk_fma_f32 v[160:161], v[72:73], 0.5, v[144:145] op_sel_hi:[1,0,1]
	v_mul_f32_e32 v144, v149, v149
	v_mul_f32_e32 v145, v151, v151
	v_pk_fma_f32 v[162:163], v[74:75], 0.5, v[146:147] op_sel_hi:[1,0,1]
	v_fmac_f32_e32 v144, v148, v148
	v_fmac_f32_e32 v145, v150, v150
	v_add_f32_e32 v144, v144, v145
	v_mul_f32_e32 v145, v161, v161
	v_mul_f32_e32 v146, v163, v163
	v_fmac_f32_e32 v145, v160, v160
	v_fmac_f32_e32 v146, v162, v162
	v_add_f32_e32 v145, v145, v146
	v_add_f32_e32 v144, v144, v145
	v_add_f32_e32 v164, v164, v144
	ds_bpermute_b32 v165, v209, v164
	v_lshl_add_u64 v[144:145], s[12:13], 0, v[200:201]
	v_lshl_add_u64 v[146:147], v[188:189], 2, v[144:145]
	global_store_dwordx4 v[146:147], v[156:159], off
	global_store_dwordx4 v[146:147], v[152:155], off offset:16
	global_store_dwordx4 v[146:147], v[148:151], off offset:512
	global_store_dwordx4 v[146:147], v[160:163], off offset:528
	s_waitcnt lgkmcnt(0)
	v_add_f32_e32 v144, v164, v165
	ds_bpermute_b32 v145, v210, v144
	s_and_saveexec_b64 s[48:49], s[4:5]
	s_cbranch_execz .LBB0_1299
	s_waitcnt lgkmcnt(0)
	v_add_f32_e32 v146, v144, v145
	v_lshl_add_u64 v[144:145], v[198:199], 2, s[40:41]
	global_atomic_add_f32 v[144:145], v146, off
.LBB0_1299:
	s_or_b64 exec, exec, s[48:49]
	v_pk_fma_f32 v[142:143], v[102:103], 0.5, v[142:143] op_sel_hi:[1,0,1]
	v_pk_fma_f32 v[140:141], v[100:101], 0.5, v[140:141] op_sel_hi:[1,0,1]
	s_waitcnt lgkmcnt(0)
	v_mul_f32_e32 v145, v143, v143
	v_mul_f32_e32 v144, v141, v141
	v_pk_fma_f32 v[138:139], v[98:99], 0.5, v[138:139] op_sel_hi:[1,0,1]
	v_pk_fma_f32 v[136:137], v[96:97], 0.5, v[136:137] op_sel_hi:[1,0,1]
	v_fmac_f32_e32 v144, v140, v140
	v_fmac_f32_e32 v145, v142, v142
	v_add_f32_e32 v144, v144, v145
	v_mul_f32_e32 v145, v137, v137
	v_mul_f32_e32 v146, v139, v139
	v_fmac_f32_e32 v145, v136, v136
	v_fmac_f32_e32 v146, v138, v138
	v_add_f32_e32 v145, v145, v146
	v_pk_fma_f32 v[134:135], v[70:71], 0.5, v[134:135] op_sel_hi:[1,0,1]
	v_pk_fma_f32 v[132:133], v[68:69], 0.5, v[132:133] op_sel_hi:[1,0,1]
	v_add_f32_e32 v148, v144, v145
	v_pk_fma_f32 v[144:145], v[64:65], 0.5, v[128:129] op_sel_hi:[1,0,1]
	v_mul_f32_e32 v128, v133, v133
	v_mul_f32_e32 v129, v135, v135
	v_pk_fma_f32 v[146:147], v[66:67], 0.5, v[130:131] op_sel_hi:[1,0,1]
	v_fmac_f32_e32 v128, v132, v132
	v_fmac_f32_e32 v129, v134, v134
	v_add_f32_e32 v128, v128, v129
	v_mul_f32_e32 v129, v145, v145
	v_mul_f32_e32 v130, v147, v147
	v_fmac_f32_e32 v129, v144, v144
	v_fmac_f32_e32 v130, v146, v146
	v_add_f32_e32 v129, v129, v130
	v_add_f32_e32 v128, v128, v129
	v_add_f32_e32 v148, v148, v128
	ds_bpermute_b32 v149, v209, v148
	v_lshl_add_u64 v[128:129], s[12:13], 0, v[196:197]
	v_lshl_add_u64 v[130:131], v[188:189], 2, v[128:129]
	global_store_dwordx4 v[130:131], v[140:143], off
	global_store_dwordx4 v[130:131], v[136:139], off offset:16
	global_store_dwordx4 v[130:131], v[132:135], off offset:512
	global_store_dwordx4 v[130:131], v[144:147], off offset:528
	s_waitcnt lgkmcnt(0)
	v_add_f32_e32 v128, v148, v149
	ds_bpermute_b32 v129, v210, v128
	s_and_saveexec_b64 s[48:49], s[4:5]
	s_cbranch_execz .LBB0_1301
	s_waitcnt lgkmcnt(0)
	v_add_f32_e32 v130, v128, v129
	v_lshl_add_u64 v[128:129], v[194:195], 2, s[40:41]
	global_atomic_add_f32 v[128:129], v130, off
.LBB0_1301:
	s_or_b64 exec, exec, s[48:49]
	v_add_u32_e32 v204, 0x80, v192
	v_ashrrev_i32_e32 v205, 31, v204
	v_add_u32_e32 v200, 0x90, v192
	v_lshlrev_b64 v[220:221], 13, v[204:205]
	v_ashrrev_i32_e32 v201, 31, v200
	v_add_u32_e32 v196, 0xa0, v192
	v_add_u32_e32 v192, 0xb0, v192
	s_waitcnt lgkmcnt(0)
	v_lshl_add_u64 v[128:129], v[190:191], 0, v[220:221]
	v_lshlrev_b64 v[202:203], 13, v[200:201]
	v_ashrrev_i32_e32 v197, 31, v196
	v_ashrrev_i32_e32 v193, 31, v192
	global_load_dwordx4 v[212:215], v[128:129], off offset:16
	global_load_dwordx4 v[216:219], v[128:129], off
	global_load_dwordx4 v[224:227], v[128:129], off offset:528
	global_load_dwordx4 v[228:231], v[128:129], off offset:512
	v_lshl_add_u64 v[128:129], v[190:191], 0, v[202:203]
	v_lshlrev_b64 v[198:199], 13, v[196:197]
	v_lshlrev_b64 v[194:195], 13, v[192:193]
	global_load_dwordx4 v[168:171], v[128:129], off offset:16
	global_load_dwordx4 v[172:175], v[128:129], off
	global_load_dwordx4 v[160:163], v[128:129], off offset:528
	global_load_dwordx4 v[164:167], v[128:129], off offset:512
	v_lshl_add_u64 v[128:129], v[190:191], 0, v[198:199]
	v_lshl_add_u64 v[132:133], v[190:191], 0, v[194:195]
	global_load_dwordx4 v[152:155], v[128:129], off offset:16
	global_load_dwordx4 v[156:159], v[128:129], off
	global_load_dwordx4 v[144:147], v[128:129], off offset:528
	global_load_dwordx4 v[148:151], v[128:129], off offset:512
	global_load_dwordx4 v[136:139], v[132:133], off offset:16
	global_load_dwordx4 v[140:143], v[132:133], off
	s_nop 0
	global_load_dwordx4 v[128:131], v[132:133], off offset:528
	s_nop 0
	global_load_dwordx4 v[132:135], v[132:133], off offset:512
	s_waitcnt vmcnt(14)
; __device__ __forceinline__ unsigned pk2(float lo, float hi) { unsigned r; asm volatile("v_cvt_pk_bf16_f32 %0, %1, %2" : "=v"(r) : "v"(lo), "v"(hi)); return r; }
; __device__ __forceinline__ float dot4(f32x4 v) { return (v[0] * v[0] + v[1] * v[1]) + (v[2] * v[2] + v[3] * v[3]); }
;     __device__ __forceinline__ void operator()(const f32x4 (&acc)[2][2][4][2], const Unit& u, int wr, int wc, int fr, int fq) const {
;     ...
;             for (int m = 0; m < 4; ++m) {
;                 const int row = row0 + ai * HALF + m * 16; const size_t off = (size_t)row * D + col0;
;                 float q = 0.f;
; #pragma unroll
;                 for (int bj = 0; bj < 2; ++bj) {
;                     if (quad >= 0 && (quad & 1) != bj) continue;
;                     const f32x4 v0 = rr[m][bj][0] + acc[ai][bj][m][0] * scale, v1 = rr[m][bj][1] + acc[ai][bj][m][1] * scale;
;                     q += dot4(v0) + dot4(v1);
;                     __builtin_nontemporal_store(v0, (f32x4*)(out + off + bj * HALF)); __builtin_nontemporal_store(v1, (f32x4*)(out + off + bj * HALF + 4));
;                     if (An) { const f32x4 a0 = v0 * gv[bj][0], a1 = v1 * gv[bj][1]; u32x4 w; w.x = pk2(a0[0], a0[1]); w.y = pk2(a0[2], a0[3]); w.z = pk2(a1[0], a1[1]); w.w = pk2(a1[2], a1[3]);
;                         *(u32x4*)(An + off + bj * HALF) = w; }
;                 }
;                 q += __shfl_xor(q, 16); q += __shfl_xor(q, 32);
;                 if (fq == 0) __hip_atomic_fetch_add(ss + row, q, __ATOMIC_RELAXED, __HIP_MEMORY_SCOPE_AGENT);
;                 __builtin_amdgcn_sched_barrier(0);
	v_pk_fma_f32 v[218:219], v[62:63], 0.5, v[218:219] op_sel_hi:[1,0,1]
	v_pk_fma_f32 v[216:217], v[60:61], 0.5, v[216:217] op_sel_hi:[1,0,1]
	v_mul_f32_e32 v191, v219, v219
	v_mul_f32_e32 v190, v217, v217
	v_pk_fma_f32 v[214:215], v[58:59], 0.5, v[214:215] op_sel_hi:[1,0,1]
	v_pk_fma_f32 v[212:213], v[56:57], 0.5, v[212:213] op_sel_hi:[1,0,1]
	v_fmac_f32_e32 v190, v216, v216
	v_fmac_f32_e32 v191, v218, v218
	v_add_f32_e32 v190, v190, v191
	v_mul_f32_e32 v191, v213, v213
	v_mul_f32_e32 v211, v215, v215
	v_fmac_f32_e32 v191, v212, v212
	v_fmac_f32_e32 v211, v214, v214
	v_add_f32_e32 v191, v191, v211
	s_waitcnt vmcnt(12)
	v_pk_fma_f32 v[230:231], v[30:31], 0.5, v[230:231] op_sel_hi:[1,0,1]
	v_pk_fma_f32 v[228:229], v[28:29], 0.5, v[228:229] op_sel_hi:[1,0,1]
	v_add_f32_e32 v190, v190, v191
	v_mul_f32_e32 v191, v229, v229
	v_mul_f32_e32 v211, v231, v231
	v_pk_fma_f32 v[226:227], v[26:27], 0.5, v[226:227] op_sel_hi:[1,0,1]
	v_pk_fma_f32 v[224:225], v[24:25], 0.5, v[224:225] op_sel_hi:[1,0,1]
	v_fmac_f32_e32 v191, v228, v228
	v_fmac_f32_e32 v211, v230, v230
	v_add_f32_e32 v191, v191, v211
	v_mul_f32_e32 v211, v225, v225
	v_mul_f32_e32 v223, v227, v227
	v_fmac_f32_e32 v211, v224, v224
	v_fmac_f32_e32 v223, v226, v226
	v_add_f32_e32 v211, v211, v223
	v_add_f32_e32 v191, v191, v211
	v_add_f32_e32 v211, v190, v191
	ds_bpermute_b32 v223, v209, v211
	v_lshl_add_u64 v[190:191], s[12:13], 0, v[220:221]
	v_lshl_add_u64 v[220:221], v[188:189], 2, v[190:191]
	global_store_dwordx4 v[220:221], v[216:219], off
	global_store_dwordx4 v[220:221], v[212:215], off offset:16
	global_store_dwordx4 v[220:221], v[228:231], off offset:512
	global_store_dwordx4 v[220:221], v[224:227], off offset:528
	s_waitcnt lgkmcnt(0)
	v_add_f32_e32 v190, v211, v223
	ds_bpermute_b32 v191, v210, v190
	s_and_saveexec_b64 s[48:49], s[4:5]
	s_cbranch_execz .LBB0_1303
	s_waitcnt lgkmcnt(0)
	v_add_f32_e32 v211, v190, v191
	v_lshl_add_u64 v[190:191], v[204:205], 2, s[40:41]
	global_atomic_add_f32 v[190:191], v211, off
.LBB0_1303:
	s_or_b64 exec, exec, s[48:49]
	s_waitcnt vmcnt(14)
	v_pk_fma_f32 v[174:175], v[54:55], 0.5, v[174:175] op_sel_hi:[1,0,1]
	v_pk_fma_f32 v[172:173], v[52:53], 0.5, v[172:173] op_sel_hi:[1,0,1]
	s_waitcnt vmcnt(12)
	v_pk_fma_f32 v[166:167], v[22:23], 0.5, v[166:167] op_sel_hi:[1,0,1]
	v_pk_fma_f32 v[164:165], v[20:21], 0.5, v[164:165] op_sel_hi:[1,0,1]
	v_mul_f32_e32 v190, v173, v173
	s_waitcnt lgkmcnt(0)
	v_mul_f32_e32 v191, v175, v175
	v_pk_fma_f32 v[212:213], v[16:17], 0.5, v[160:161] op_sel_hi:[1,0,1]
	v_mul_f32_e32 v160, v165, v165
	v_mul_f32_e32 v161, v167, v167
	v_pk_fma_f32 v[170:171], v[50:51], 0.5, v[170:171] op_sel_hi:[1,0,1]
	v_pk_fma_f32 v[168:169], v[48:49], 0.5, v[168:169] op_sel_hi:[1,0,1]
	v_fmac_f32_e32 v190, v172, v172
	v_fmac_f32_e32 v191, v174, v174
	v_pk_fma_f32 v[214:215], v[18:19], 0.5, v[162:163] op_sel_hi:[1,0,1]
	v_fmac_f32_e32 v160, v164, v164
	v_fmac_f32_e32 v161, v166, v166
	v_add_f32_e32 v190, v190, v191
	v_mul_f32_e32 v191, v169, v169
	v_mul_f32_e32 v204, v171, v171
	v_add_f32_e32 v160, v160, v161
	v_mul_f32_e32 v161, v213, v213
	v_mul_f32_e32 v162, v215, v215
	v_fmac_f32_e32 v191, v168, v168
	v_fmac_f32_e32 v204, v170, v170
	v_fmac_f32_e32 v161, v212, v212
	v_fmac_f32_e32 v162, v214, v214
	v_add_f32_e32 v191, v191, v204
	v_add_f32_e32 v161, v161, v162
	v_add_f32_e32 v190, v190, v191
	v_add_f32_e32 v160, v160, v161
	v_add_f32_e32 v190, v190, v160
	ds_bpermute_b32 v191, v209, v190
	v_lshl_add_u64 v[160:161], s[12:13], 0, v[202:203]
	v_lshl_add_u64 v[162:163], v[188:189], 2, v[160:161]
	global_store_dwordx4 v[162:163], v[172:175], off
	global_store_dwordx4 v[162:163], v[168:171], off offset:16
	global_store_dwordx4 v[162:163], v[164:167], off offset:512
	global_store_dwordx4 v[162:163], v[212:215], off offset:528
	s_waitcnt lgkmcnt(0)
	v_add_f32_e32 v160, v190, v191
	ds_bpermute_b32 v161, v210, v160
	s_and_saveexec_b64 s[48:49], s[4:5]
	s_cbranch_execz .LBB0_1305
	s_waitcnt lgkmcnt(0)
	v_add_f32_e32 v162, v160, v161
	v_lshl_add_u64 v[160:161], v[200:201], 2, s[40:41]
	global_atomic_add_f32 v[160:161], v162, off
; __device__ __forceinline__ unsigned pk2(float lo, float hi) { unsigned r; asm volatile("v_cvt_pk_bf16_f32 %0, %1, %2" : "=v"(r) : "v"(lo), "v"(hi)); return r; }
; __device__ __forceinline__ float dot4(f32x4 v) { return (v[0] * v[0] + v[1] * v[1]) + (v[2] * v[2] + v[3] * v[3]); }
;     __device__ __forceinline__ void operator()(const f32x4 (&acc)[2][2][4][2], const Unit& u, int wr, int wc, int fr, int fq) const {
;     ...
;             for (int m = 0; m < 4; ++m) {
;                 const int row = row0 + ai * HALF + m * 16; const size_t off = (size_t)row * D + col0;
;                 float q = 0.f;
; #pragma unroll
;                 for (int bj = 0; bj < 2; ++bj) {
;                     if (quad >= 0 && (quad & 1) != bj) continue;
;                     const f32x4 v0 = rr[m][bj][0] + acc[ai][bj][m][0] * scale, v1 = rr[m][bj][1] + acc[ai][bj][m][1] * scale;
;                     q += dot4(v0) + dot4(v1);
;                     __builtin_nontemporal_store(v0, (f32x4*)(out + off + bj * HALF)); __builtin_nontemporal_store(v1, (f32x4*)(out + off + bj * HALF + 4));
;                     if (An) { const f32x4 a0 = v0 * gv[bj][0], a1 = v1 * gv[bj][1]; u32x4 w; w.x = pk2(a0[0], a0[1]); w.y = pk2(a0[2], a0[3]); w.z = pk2(a1[0], a1[1]); w.w = pk2(a1[2], a1[3]);
;                         *(u32x4*)(An + off + bj * HALF) = w; }
;                 }
;                 q += __shfl_xor(q, 16); q += __shfl_xor(q, 32);
;                 if (fq == 0) __hip_atomic_fetch_add(ss + row, q, __ATOMIC_RELAXED, __HIP_MEMORY_SCOPE_AGENT);
;                 __builtin_amdgcn_sched_barrier(0);
.LBB0_1305:
	s_or_b64 exec, exec, s[48:49]
	s_waitcnt vmcnt(14)
	v_pk_fma_f32 v[158:159], v[46:47], 0.5, v[158:159] op_sel_hi:[1,0,1]
	v_pk_fma_f32 v[156:157], v[44:45], 0.5, v[156:157] op_sel_hi:[1,0,1]
	s_waitcnt lgkmcnt(0)
	v_mul_f32_e32 v161, v159, v159
	v_mul_f32_e32 v160, v157, v157
	v_pk_fma_f32 v[154:155], v[42:43], 0.5, v[154:155] op_sel_hi:[1,0,1]
	v_pk_fma_f32 v[152:153], v[40:41], 0.5, v[152:153] op_sel_hi:[1,0,1]
	v_fmac_f32_e32 v160, v156, v156
	v_fmac_f32_e32 v161, v158, v158
	v_add_f32_e32 v160, v160, v161
	v_mul_f32_e32 v161, v153, v153
	v_mul_f32_e32 v162, v155, v155
	v_fmac_f32_e32 v161, v152, v152
	v_fmac_f32_e32 v162, v154, v154
	v_add_f32_e32 v161, v161, v162
	s_waitcnt vmcnt(12)
	v_pk_fma_f32 v[150:151], v[14:15], 0.5, v[150:151] op_sel_hi:[1,0,1]
	v_pk_fma_f32 v[148:149], v[12:13], 0.5, v[148:149] op_sel_hi:[1,0,1]
	v_add_f32_e32 v164, v160, v161
	v_pk_fma_f32 v[160:161], v[8:9], 0.5, v[144:145] op_sel_hi:[1,0,1]
	v_mul_f32_e32 v144, v149, v149
	v_mul_f32_e32 v145, v151, v151
	v_pk_fma_f32 v[162:163], v[10:11], 0.5, v[146:147] op_sel_hi:[1,0,1]
	v_fmac_f32_e32 v144, v148, v148
	v_fmac_f32_e32 v145, v150, v150
	v_add_f32_e32 v144, v144, v145
	v_mul_f32_e32 v145, v161, v161
	v_mul_f32_e32 v146, v163, v163
	v_fmac_f32_e32 v145, v160, v160
	v_fmac_f32_e32 v146, v162, v162
	v_add_f32_e32 v145, v145, v146
	v_add_f32_e32 v144, v144, v145
	v_add_f32_e32 v164, v164, v144
	ds_bpermute_b32 v165, v209, v164
	v_lshl_add_u64 v[144:145], s[12:13], 0, v[198:199]
	v_lshl_add_u64 v[146:147], v[188:189], 2, v[144:145]
	global_store_dwordx4 v[146:147], v[156:159], off
	global_store_dwordx4 v[146:147], v[152:155], off offset:16
	global_store_dwordx4 v[146:147], v[148:151], off offset:512
	global_store_dwordx4 v[146:147], v[160:163], off offset:528
	s_waitcnt lgkmcnt(0)
	v_add_f32_e32 v144, v164, v165
	ds_bpermute_b32 v145, v210, v144
	s_and_saveexec_b64 s[48:49], s[4:5]
	s_cbranch_execz .LBB0_1307
	s_waitcnt lgkmcnt(0)
	v_add_f32_e32 v146, v144, v145
	v_lshl_add_u64 v[144:145], v[196:197], 2, s[40:41]
	global_atomic_add_f32 v[144:145], v146, off
.LBB0_1307:
	s_or_b64 exec, exec, s[48:49]
	s_waitcnt vmcnt(14)
	v_pk_fma_f32 v[142:143], v[38:39], 0.5, v[142:143] op_sel_hi:[1,0,1]
	v_pk_fma_f32 v[140:141], v[36:37], 0.5, v[140:141] op_sel_hi:[1,0,1]
	s_waitcnt lgkmcnt(0)
	v_mul_f32_e32 v145, v143, v143
	v_mul_f32_e32 v144, v141, v141
	v_pk_fma_f32 v[138:139], v[34:35], 0.5, v[138:139] op_sel_hi:[1,0,1]
	v_pk_fma_f32 v[136:137], v[32:33], 0.5, v[136:137] op_sel_hi:[1,0,1]
	v_fmac_f32_e32 v144, v140, v140
	v_fmac_f32_e32 v145, v142, v142
	v_add_f32_e32 v144, v144, v145
	v_mul_f32_e32 v145, v137, v137
	v_mul_f32_e32 v146, v139, v139
	v_fmac_f32_e32 v145, v136, v136
	v_fmac_f32_e32 v146, v138, v138
	v_add_f32_e32 v145, v145, v146
	s_waitcnt vmcnt(12)
	v_pk_fma_f32 v[134:135], v[6:7], 0.5, v[134:135] op_sel_hi:[1,0,1]
	v_pk_fma_f32 v[132:133], v[4:5], 0.5, v[132:133] op_sel_hi:[1,0,1]
	v_add_f32_e32 v148, v144, v145
	v_pk_fma_f32 v[144:145], v[0:1], 0.5, v[128:129] op_sel_hi:[1,0,1]
	v_mul_f32_e32 v128, v133, v133
	v_mul_f32_e32 v129, v135, v135
	v_pk_fma_f32 v[146:147], v[2:3], 0.5, v[130:131] op_sel_hi:[1,0,1]
	v_fmac_f32_e32 v128, v132, v132
	v_fmac_f32_e32 v129, v134, v134
	v_add_f32_e32 v128, v128, v129
	v_mul_f32_e32 v129, v145, v145
	v_mul_f32_e32 v130, v147, v147
	v_fmac_f32_e32 v129, v144, v144
	v_fmac_f32_e32 v130, v146, v146
	v_add_f32_e32 v129, v129, v130
	v_add_f32_e32 v128, v128, v129
	v_add_f32_e32 v148, v148, v128
	ds_bpermute_b32 v149, v209, v148
	v_lshl_add_u64 v[128:129], s[12:13], 0, v[194:195]
	v_lshl_add_u64 v[130:131], v[188:189], 2, v[128:129]
	global_store_dwordx4 v[130:131], v[140:143], off
	global_store_dwordx4 v[130:131], v[136:139], off offset:16
	global_store_dwordx4 v[130:131], v[132:135], off offset:512
	global_store_dwordx4 v[130:131], v[144:147], off offset:528
	s_waitcnt lgkmcnt(0)
	v_add_f32_e32 v128, v148, v149
	ds_bpermute_b32 v129, v210, v128
	s_and_saveexec_b64 s[48:49], s[4:5]
	s_cbranch_execz .LBB0_1309
	s_waitcnt lgkmcnt(0)
	v_add_f32_e32 v130, v128, v129
	v_lshl_add_u64 v[128:129], v[192:193], 2, s[40:41]
	global_atomic_add_f32 v[128:129], v130, off

; __device__ __forceinline__ unsigned pk2(float lo, float hi) { unsigned r; asm volatile("v_cvt_pk_bf16_f32 %0, %1, %2" : "=v"(r) : "v"(lo), "v"(hi)); return r; }
; __device__ __forceinline__ float dot4(f32x4 v) { return (v[0] * v[0] + v[1] * v[1]) + (v[2] * v[2] + v[3] * v[3]); }
;     __device__ __forceinline__ void operator()(const f32x4 (&acc)[2][2][4][2], const Unit& u, int wr, int wc, int fr, int fq) const {
;     ...
;                 const int row = row0 + ai * HALF + m * 16; const size_t off = (size_t)row * D + col0;
;                 float q = 0.f;
; #pragma unroll
;                 for (int bj = 0; bj < 2; ++bj) {
;                     if (quad >= 0 && (quad & 1) != bj) continue;
;                     const f32x4 v0 = rr[m][bj][0] + acc[ai][bj][m][0] * scale, v1 = rr[m][bj][1] + acc[ai][bj][m][1] * scale;
;                     q += dot4(v0) + dot4(v1);
;                     __builtin_nontemporal_store(v0, (f32x4*)(out + off + bj * HALF)); __builtin_nontemporal_store(v1, (f32x4*)(out + off + bj * HALF + 4));
;                     if (An) { const f32x4 a0 = v0 * gv[bj][0], a1 = v1 * gv[bj][1]; u32x4 w; w.x = pk2(a0[0], a0[1]); w.y = pk2(a0[2], a0[3]); w.z = pk2(a1[0], a1[1]); w.w = pk2(a1[2], a1[3]);
;                         *(u32x4*)(An + off + bj * HALF) = w; }
;                 }
; __device__ __forceinline__ void ph_res_fix(int ph) {
;     ...
;                 for (int n = 0; n < 2; ++n) if (a * 2 + b == quad) acc[a][b][m][n] = s[m * 2 + n];
.LBB0_1384:
	s_cmp_eq_u32 s16, 0
	s_cselect_b64 s[10:11], -1, 0
	v_lshlrev_b64 v[108:109], 11, v[100:101]
	v_lshl_add_u64 v[108:109], v[108:109], 0, v[76:77]
	v_mov_b32_e32 v110, 0
	s_and_b64 vcc, exec, s[8:9]
	v_lshl_add_u64 v[108:109], v[108:109], 2, s[20:21]
	s_cbranch_vccnz .LBB0_1386
	v_pk_mul_f32 v[112:113], v[94:95], 0.5 op_sel_hi:[1,0]
	v_pk_mul_f32 v[110:111], v[88:89], 0.5 op_sel_hi:[1,0]
	v_cndmask_b32_e64 v113, 0, v113, s[10:11]
	v_cndmask_b32_e64 v112, 0, v112, s[10:11]
	v_cndmask_b32_e64 v111, 0, v111, s[10:11]
	v_cndmask_b32_e64 v110, 0, v110, s[10:11]
	s_waitcnt vmcnt(0)
	v_pk_add_f32 v[60:61], v[60:61], v[112:113]
	v_pk_mul_f32 v[112:113], v[96:97], 0.5 op_sel_hi:[1,0]
	v_pk_add_f32 v[62:63], v[62:63], v[110:111]
	v_pk_mul_f32 v[110:111], v[90:91], 0.5 op_sel_hi:[1,0]
	v_cndmask_b32_e64 v113, 0, v113, s[10:11]
	v_cndmask_b32_e64 v112, 0, v112, s[10:11]
	v_cndmask_b32_e64 v111, 0, v111, s[10:11]
	v_cndmask_b32_e64 v110, 0, v110, s[10:11]
	v_pk_add_f32 v[52:53], v[52:53], v[112:113]
	v_pk_add_f32 v[54:55], v[54:55], v[110:111]
	v_mov_b32_e32 v112, v61
	v_mov_b32_e32 v113, v53
	v_mov_b32_e32 v110, v60
	v_mov_b32_e32 v111, v52
	v_pk_mul_f32 v[112:113], v[112:113], v[112:113]
	v_mov_b32_e32 v114, v63
	v_mov_b32_e32 v115, v55
	v_pk_fma_f32 v[110:111], v[110:111], v[110:111], v[112:113]
	v_mov_b32_e32 v112, v62
	v_mov_b32_e32 v113, v54
	v_pk_mul_f32 v[114:115], v[114:115], v[114:115]
	global_store_dwordx4 v[108:109], v[60:63], off
	global_store_dwordx4 v[108:109], v[52:55], off offset:16
	v_pk_fma_f32 v[112:113], v[112:113], v[112:113], v[114:115]
	s_nop 0
	v_pk_add_f32 v[110:111], v[110:111], v[112:113]
	s_nop 0
	v_add_f32_e32 v110, v110, v111
.LBB0_1386:
	s_cmp_eq_u32 s16, 1
	s_cselect_b64 s[12:13], -1, 0
	s_and_b64 vcc, exec, s[6:7]
	s_cbranch_vccnz .LBB0_1388
	s_waitcnt vmcnt(1)
	v_pk_mul_f32 v[52:53], v[88:89], 0.5 op_sel_hi:[1,0]
	v_pk_mul_f32 v[54:55], v[94:95], 0.5 op_sel_hi:[1,0]
	s_waitcnt vmcnt(0)
	v_cndmask_b32_e64 v61, 0, v53, s[12:13]
	v_cndmask_b32_e64 v55, 0, v55, s[12:13]
	v_cndmask_b32_e64 v54, 0, v54, s[12:13]
	v_cndmask_b32_e64 v60, 0, v52, s[12:13]
	v_pk_add_f32 v[52:53], v[56:57], v[54:55]
	v_pk_add_f32 v[54:55], v[58:59], v[60:61]
	v_pk_mul_f32 v[58:59], v[96:97], 0.5 op_sel_hi:[1,0]
	v_pk_mul_f32 v[56:57], v[90:91], 0.5 op_sel_hi:[1,0]
	v_cndmask_b32_e64 v59, 0, v59, s[12:13]
	v_cndmask_b32_e64 v58, 0, v58, s[12:13]
	v_cndmask_b32_e64 v57, 0, v57, s[12:13]
	v_cndmask_b32_e64 v56, 0, v56, s[12:13]
	v_pk_add_f32 v[44:45], v[44:45], v[58:59]
	v_pk_add_f32 v[46:47], v[46:47], v[56:57]
	v_mov_b32_e32 v58, v53
	v_mov_b32_e32 v59, v45
	v_mov_b32_e32 v56, v52
	v_mov_b32_e32 v57, v44
	v_pk_mul_f32 v[58:59], v[58:59], v[58:59]
	v_mov_b32_e32 v60, v55
	v_mov_b32_e32 v61, v47
	v_pk_fma_f32 v[56:57], v[56:57], v[56:57], v[58:59]
	v_mov_b32_e32 v58, v54
	v_mov_b32_e32 v59, v46
	v_pk_mul_f32 v[60:61], v[60:61], v[60:61]
	global_store_dwordx4 v[108:109], v[52:55], off offset:512
	global_store_dwordx4 v[108:109], v[44:47], off offset:528
	v_pk_fma_f32 v[58:59], v[58:59], v[58:59], v[60:61]
	s_nop 0
	v_pk_add_f32 v[56:57], v[56:57], v[58:59]
	s_nop 0
	v_add_f32_e32 v56, v56, v57
	v_add_f32_e32 v110, v110, v56

; __device__ __forceinline__ unsigned pk2(float lo, float hi) { unsigned r; asm volatile("v_cvt_pk_bf16_f32 %0, %1, %2" : "=v"(r) : "v"(lo), "v"(hi)); return r; }
; __device__ __forceinline__ float dot4(f32x4 v) { return (v[0] * v[0] + v[1] * v[1]) + (v[2] * v[2] + v[3] * v[3]); }
;     __device__ __forceinline__ void operator()(const f32x4 (&acc)[2][2][4][2], const Unit& u, int wr, int wc, int fr, int fq) const {
;     ...
;                 const int row = row0 + ai * HALF + m * 16; const size_t off = (size_t)row * D + col0;
;                 float q = 0.f;
; #pragma unroll
;                 for (int bj = 0; bj < 2; ++bj) {
;                     if (quad >= 0 && (quad & 1) != bj) continue;
;                     const f32x4 v0 = rr[m][bj][0] + acc[ai][bj][m][0] * scale, v1 = rr[m][bj][1] + acc[ai][bj][m][1] * scale;
;                     q += dot4(v0) + dot4(v1);
;                     __builtin_nontemporal_store(v0, (f32x4*)(out + off + bj * HALF)); __builtin_nontemporal_store(v1, (f32x4*)(out + off + bj * HALF + 4));
;                     if (An) { const f32x4 a0 = v0 * gv[bj][0], a1 = v1 * gv[bj][1]; u32x4 w; w.x = pk2(a0[0], a0[1]); w.y = pk2(a0[2], a0[3]); w.z = pk2(a1[0], a1[1]); w.w = pk2(a1[2], a1[3]);
;                         *(u32x4*)(An + off + bj * HALF) = w; }
;                 }
; __device__ __forceinline__ void ph_res_fix(int ph) {
;     ...
;                 for (int n = 0; n < 2; ++n) if (a * 2 + b == quad) acc[a][b][m][n] = s[m * 2 + n];
.LBB0_1390:
	s_or_b64 exec, exec, s[14:15]
	s_waitcnt lgkmcnt(0)
	v_lshlrev_b64 v[44:45], 11, v[106:107]
	v_lshl_add_u64 v[44:45], v[44:45], 0, v[76:77]
	v_mov_b32_e32 v52, 0
	s_and_b64 vcc, exec, s[8:9]
	v_lshl_add_u64 v[44:45], v[44:45], 2, s[20:21]
	s_cbranch_vccnz .LBB0_1392
	v_pk_mul_f32 v[54:55], v[86:87], 0.5 op_sel_hi:[1,0]
	v_pk_mul_f32 v[52:53], v[78:79], 0.5 op_sel_hi:[1,0]
	v_cndmask_b32_e64 v55, 0, v55, s[10:11]
	v_cndmask_b32_e64 v54, 0, v54, s[10:11]
	v_cndmask_b32_e64 v53, 0, v53, s[10:11]
	v_cndmask_b32_e64 v52, 0, v52, s[10:11]
	s_waitcnt vmcnt(0)
	v_pk_add_f32 v[48:49], v[48:49], v[54:55]
	v_pk_mul_f32 v[54:55], v[92:93], 0.5 op_sel_hi:[1,0]
	v_pk_add_f32 v[50:51], v[50:51], v[52:53]
	v_pk_mul_f32 v[52:53], v[82:83], 0.5 op_sel_hi:[1,0]
	v_cndmask_b32_e64 v55, 0, v55, s[10:11]
	v_cndmask_b32_e64 v54, 0, v54, s[10:11]
	v_cndmask_b32_e64 v53, 0, v53, s[10:11]
	v_cndmask_b32_e64 v52, 0, v52, s[10:11]
	v_pk_add_f32 v[40:41], v[40:41], v[54:55]
	v_pk_add_f32 v[42:43], v[42:43], v[52:53]
	v_mov_b32_e32 v54, v49
	v_mov_b32_e32 v55, v41
	v_mov_b32_e32 v52, v48
	v_mov_b32_e32 v53, v40
	v_pk_mul_f32 v[54:55], v[54:55], v[54:55]
	v_mov_b32_e32 v56, v51
	v_mov_b32_e32 v57, v43
	v_pk_fma_f32 v[52:53], v[52:53], v[52:53], v[54:55]
	v_mov_b32_e32 v54, v50
	v_mov_b32_e32 v55, v42
	v_pk_mul_f32 v[56:57], v[56:57], v[56:57]
	global_store_dwordx4 v[44:45], v[48:51], off
	global_store_dwordx4 v[44:45], v[40:43], off offset:16
	v_pk_fma_f32 v[54:55], v[54:55], v[54:55], v[56:57]
	s_nop 0
	v_pk_add_f32 v[52:53], v[52:53], v[54:55]
	s_nop 0
	v_add_f32_e32 v52, v52, v53
.LBB0_1392:
	s_and_b64 vcc, exec, s[6:7]
	s_cbranch_vccnz .LBB0_1394
	v_pk_mul_f32 v[42:43], v[86:87], 0.5 op_sel_hi:[1,0]
	v_pk_mul_f32 v[40:41], v[78:79], 0.5 op_sel_hi:[1,0]
	v_cndmask_b32_e64 v43, 0, v43, s[12:13]
	v_cndmask_b32_e64 v42, 0, v42, s[12:13]
	v_cndmask_b32_e64 v41, 0, v41, s[12:13]
	v_cndmask_b32_e64 v40, 0, v40, s[12:13]
	s_waitcnt vmcnt(0)
	v_pk_add_f32 v[36:37], v[36:37], v[42:43]
	v_pk_mul_f32 v[42:43], v[92:93], 0.5 op_sel_hi:[1,0]
	v_pk_add_f32 v[38:39], v[38:39], v[40:41]
	v_pk_mul_f32 v[40:41], v[82:83], 0.5 op_sel_hi:[1,0]
	v_cndmask_b32_e64 v43, 0, v43, s[12:13]
	v_cndmask_b32_e64 v42, 0, v42, s[12:13]
	v_cndmask_b32_e64 v41, 0, v41, s[12:13]
	v_cndmask_b32_e64 v40, 0, v40, s[12:13]
	v_pk_add_f32 v[28:29], v[28:29], v[42:43]
	v_pk_add_f32 v[30:31], v[30:31], v[40:41]
	v_mov_b32_e32 v42, v37
	v_mov_b32_e32 v43, v29
	v_mov_b32_e32 v40, v36
	v_mov_b32_e32 v41, v28
	v_pk_mul_f32 v[42:43], v[42:43], v[42:43]
	v_mov_b32_e32 v48, v39
	v_mov_b32_e32 v49, v31
	v_pk_fma_f32 v[40:41], v[40:41], v[40:41], v[42:43]
	v_mov_b32_e32 v42, v38
	v_mov_b32_e32 v43, v30
	v_pk_mul_f32 v[48:49], v[48:49], v[48:49]
	global_store_dwordx4 v[44:45], v[36:39], off offset:512
	global_store_dwordx4 v[44:45], v[28:31], off offset:528
	v_pk_fma_f32 v[42:43], v[42:43], v[42:43], v[48:49]
	s_nop 0
	v_pk_add_f32 v[40:41], v[40:41], v[42:43]
	s_nop 0
	v_add_f32_e32 v40, v40, v41
	v_add_f32_e32 v52, v52, v40

; __device__ __forceinline__ unsigned pk2(float lo, float hi) { unsigned r; asm volatile("v_cvt_pk_bf16_f32 %0, %1, %2" : "=v"(r) : "v"(lo), "v"(hi)); return r; }
; __device__ __forceinline__ float dot4(f32x4 v) { return (v[0] * v[0] + v[1] * v[1]) + (v[2] * v[2] + v[3] * v[3]); }
;     __device__ __forceinline__ void operator()(const f32x4 (&acc)[2][2][4][2], const Unit& u, int wr, int wc, int fr, int fq) const {
;     ...
;                 const int row = row0 + ai * HALF + m * 16; const size_t off = (size_t)row * D + col0;
;                 float q = 0.f;
; #pragma unroll
;                 for (int bj = 0; bj < 2; ++bj) {
;                     if (quad >= 0 && (quad & 1) != bj) continue;
;                     const f32x4 v0 = rr[m][bj][0] + acc[ai][bj][m][0] * scale, v1 = rr[m][bj][1] + acc[ai][bj][m][1] * scale;
;                     q += dot4(v0) + dot4(v1);
;                     __builtin_nontemporal_store(v0, (f32x4*)(out + off + bj * HALF)); __builtin_nontemporal_store(v1, (f32x4*)(out + off + bj * HALF + 4));
;                     if (An) { const f32x4 a0 = v0 * gv[bj][0], a1 = v1 * gv[bj][1]; u32x4 w; w.x = pk2(a0[0], a0[1]); w.y = pk2(a0[2], a0[3]); w.z = pk2(a1[0], a1[1]); w.w = pk2(a1[2], a1[3]);
;                         *(u32x4*)(An + off + bj * HALF) = w; }
;                 }
; __device__ __forceinline__ void ph_res_fix(int ph) {
;     ...
;                 for (int n = 0; n < 2; ++n) if (a * 2 + b == quad) acc[a][b][m][n] = s[m * 2 + n];
.LBB0_1396:
	s_or_b64 exec, exec, s[14:15]
	s_waitcnt lgkmcnt(0)
	v_lshlrev_b64 v[28:29], 11, v[104:105]
	v_lshl_add_u64 v[28:29], v[28:29], 0, v[76:77]
	v_mov_b32_e32 v30, 0
	s_and_b64 vcc, exec, s[8:9]
	v_lshl_add_u64 v[28:29], v[28:29], 2, s[20:21]
	s_cbranch_vccnz .LBB0_1398
	s_waitcnt vmcnt(0)
	v_pk_mul_f32 v[36:37], v[80:81], 0.5 op_sel_hi:[1,0]
	v_pk_mul_f32 v[30:31], v[68:69], 0.5 op_sel_hi:[1,0]
	v_cndmask_b32_e64 v37, 0, v37, s[10:11]
	v_cndmask_b32_e64 v36, 0, v36, s[10:11]
	v_cndmask_b32_e64 v31, 0, v31, s[10:11]
	v_cndmask_b32_e64 v30, 0, v30, s[10:11]
	v_pk_add_f32 v[32:33], v[32:33], v[36:37]
	v_pk_mul_f32 v[36:37], v[84:85], 0.5 op_sel_hi:[1,0]
	v_pk_add_f32 v[34:35], v[34:35], v[30:31]
	v_pk_mul_f32 v[30:31], v[72:73], 0.5 op_sel_hi:[1,0]
	v_cndmask_b32_e64 v37, 0, v37, s[10:11]
	v_cndmask_b32_e64 v36, 0, v36, s[10:11]
	v_cndmask_b32_e64 v31, 0, v31, s[10:11]
	v_cndmask_b32_e64 v30, 0, v30, s[10:11]
	v_pk_add_f32 v[24:25], v[24:25], v[36:37]
	v_pk_add_f32 v[26:27], v[26:27], v[30:31]
	v_mov_b32_e32 v36, v33
	v_mov_b32_e32 v37, v25
	v_mov_b32_e32 v30, v32
	v_mov_b32_e32 v31, v24
	v_pk_mul_f32 v[36:37], v[36:37], v[36:37]
	v_mov_b32_e32 v38, v35
	v_mov_b32_e32 v39, v27
	v_pk_fma_f32 v[30:31], v[30:31], v[30:31], v[36:37]
	v_mov_b32_e32 v36, v34
	v_mov_b32_e32 v37, v26
	v_pk_mul_f32 v[38:39], v[38:39], v[38:39]
	global_store_dwordx4 v[28:29], v[32:35], off
	global_store_dwordx4 v[28:29], v[24:27], off offset:16
	v_pk_fma_f32 v[36:37], v[36:37], v[36:37], v[38:39]
	s_nop 0
	v_pk_add_f32 v[30:31], v[30:31], v[36:37]
	s_nop 0
	v_add_f32_e32 v30, v30, v31
.LBB0_1398:
	s_and_b64 vcc, exec, s[6:7]
	s_cbranch_vccnz .LBB0_1400
	v_pk_mul_f32 v[26:27], v[80:81], 0.5 op_sel_hi:[1,0]
	v_pk_mul_f32 v[24:25], v[68:69], 0.5 op_sel_hi:[1,0]
	v_cndmask_b32_e64 v27, 0, v27, s[12:13]
	v_cndmask_b32_e64 v26, 0, v26, s[12:13]
	v_cndmask_b32_e64 v25, 0, v25, s[12:13]
	v_cndmask_b32_e64 v24, 0, v24, s[12:13]
	s_waitcnt vmcnt(0)
	v_pk_add_f32 v[20:21], v[20:21], v[26:27]
	v_pk_mul_f32 v[26:27], v[84:85], 0.5 op_sel_hi:[1,0]
	v_pk_add_f32 v[22:23], v[22:23], v[24:25]
	v_pk_mul_f32 v[24:25], v[72:73], 0.5 op_sel_hi:[1,0]
	v_cndmask_b32_e64 v27, 0, v27, s[12:13]
	v_cndmask_b32_e64 v26, 0, v26, s[12:13]
	v_cndmask_b32_e64 v25, 0, v25, s[12:13]
	v_cndmask_b32_e64 v24, 0, v24, s[12:13]
	v_pk_add_f32 v[12:13], v[12:13], v[26:27]
	v_pk_add_f32 v[14:15], v[14:15], v[24:25]
	v_mov_b32_e32 v26, v21
	v_mov_b32_e32 v27, v13
	v_mov_b32_e32 v24, v20
	v_mov_b32_e32 v25, v12
	v_pk_mul_f32 v[26:27], v[26:27], v[26:27]
	v_mov_b32_e32 v32, v23
	v_mov_b32_e32 v33, v15
	v_pk_fma_f32 v[24:25], v[24:25], v[24:25], v[26:27]
	v_mov_b32_e32 v26, v22
	v_mov_b32_e32 v27, v14
	v_pk_mul_f32 v[32:33], v[32:33], v[32:33]
	global_store_dwordx4 v[28:29], v[20:23], off offset:512
	global_store_dwordx4 v[28:29], v[12:15], off offset:528
	v_pk_fma_f32 v[26:27], v[26:27], v[26:27], v[32:33]
	s_nop 0
	v_pk_add_f32 v[24:25], v[24:25], v[26:27]
	s_nop 0
	v_add_f32_e32 v24, v24, v25
	v_add_f32_e32 v30, v30, v24

; __device__ __forceinline__ unsigned pk2(float lo, float hi) { unsigned r; asm volatile("v_cvt_pk_bf16_f32 %0, %1, %2" : "=v"(r) : "v"(lo), "v"(hi)); return r; }
; __device__ __forceinline__ float dot4(f32x4 v) { return (v[0] * v[0] + v[1] * v[1]) + (v[2] * v[2] + v[3] * v[3]); }
;     __device__ __forceinline__ void operator()(const f32x4 (&acc)[2][2][4][2], const Unit& u, int wr, int wc, int fr, int fq) const {
;     ...
;                 const int row = row0 + ai * HALF + m * 16; const size_t off = (size_t)row * D + col0;
;                 float q = 0.f;
; #pragma unroll
;                 for (int bj = 0; bj < 2; ++bj) {
;                     if (quad >= 0 && (quad & 1) != bj) continue;
;                     const f32x4 v0 = rr[m][bj][0] + acc[ai][bj][m][0] * scale, v1 = rr[m][bj][1] + acc[ai][bj][m][1] * scale;
;                     q += dot4(v0) + dot4(v1);
;                     __builtin_nontemporal_store(v0, (f32x4*)(out + off + bj * HALF)); __builtin_nontemporal_store(v1, (f32x4*)(out + off + bj * HALF + 4));
;                     if (An) { const f32x4 a0 = v0 * gv[bj][0], a1 = v1 * gv[bj][1]; u32x4 w; w.x = pk2(a0[0], a0[1]); w.y = pk2(a0[2], a0[3]); w.z = pk2(a1[0], a1[1]); w.w = pk2(a1[2], a1[3]);
;                         *(u32x4*)(An + off + bj * HALF) = w; }
;                 }
; __device__ __forceinline__ void ph_res_fix(int ph) {
;     ...
;                 for (int n = 0; n < 2; ++n) if (a * 2 + b == quad) acc[a][b][m][n] = s[m * 2 + n];
.LBB0_1402:
	s_or_b64 exec, exec, s[14:15]
	s_waitcnt lgkmcnt(0)
	v_lshlrev_b64 v[12:13], 11, v[102:103]
	v_lshl_add_u64 v[12:13], v[12:13], 0, v[76:77]
	v_mov_b32_e32 v14, 0
	s_and_b64 vcc, exec, s[8:9]
	v_lshl_add_u64 v[12:13], v[12:13], 2, s[20:21]
	s_cbranch_vccnz .LBB0_1404
	s_waitcnt vmcnt(0)
	v_pk_mul_f32 v[20:21], v[70:71], 0.5 op_sel_hi:[1,0]
	v_pk_mul_f32 v[14:15], v[64:65], 0.5 op_sel_hi:[1,0]
	v_cndmask_b32_e64 v21, 0, v21, s[10:11]
	v_cndmask_b32_e64 v20, 0, v20, s[10:11]
	v_cndmask_b32_e64 v15, 0, v15, s[10:11]
	v_cndmask_b32_e64 v14, 0, v14, s[10:11]
	v_pk_add_f32 v[16:17], v[16:17], v[20:21]
	v_pk_mul_f32 v[20:21], v[74:75], 0.5 op_sel_hi:[1,0]
	v_pk_add_f32 v[18:19], v[18:19], v[14:15]
	v_pk_mul_f32 v[14:15], v[66:67], 0.5 op_sel_hi:[1,0]
	v_cndmask_b32_e64 v21, 0, v21, s[10:11]
	v_cndmask_b32_e64 v20, 0, v20, s[10:11]
	v_cndmask_b32_e64 v15, 0, v15, s[10:11]
	v_cndmask_b32_e64 v14, 0, v14, s[10:11]
	v_pk_add_f32 v[8:9], v[8:9], v[20:21]
	v_pk_add_f32 v[10:11], v[10:11], v[14:15]
	v_mov_b32_e32 v20, v17
	v_mov_b32_e32 v21, v9
	v_mov_b32_e32 v14, v16
	v_mov_b32_e32 v15, v8
	v_pk_mul_f32 v[20:21], v[20:21], v[20:21]
	v_mov_b32_e32 v22, v19
	v_mov_b32_e32 v23, v11
	v_pk_fma_f32 v[14:15], v[14:15], v[14:15], v[20:21]
	v_mov_b32_e32 v20, v18
	v_mov_b32_e32 v21, v10
	v_pk_mul_f32 v[22:23], v[22:23], v[22:23]
	global_store_dwordx4 v[12:13], v[16:19], off
	global_store_dwordx4 v[12:13], v[8:11], off offset:16
	v_pk_fma_f32 v[20:21], v[20:21], v[20:21], v[22:23]
	s_nop 0
	v_pk_add_f32 v[14:15], v[14:15], v[20:21]
	s_nop 0
	v_add_f32_e32 v14, v14, v15
.LBB0_1404:
	s_and_b64 vcc, exec, s[6:7]
	s_cbranch_vccnz .LBB0_1406
	v_pk_mul_f32 v[10:11], v[70:71], 0.5 op_sel_hi:[1,0]
	v_pk_mul_f32 v[8:9], v[64:65], 0.5 op_sel_hi:[1,0]
	v_cndmask_b32_e64 v11, 0, v11, s[12:13]
	v_cndmask_b32_e64 v10, 0, v10, s[12:13]
	v_cndmask_b32_e64 v9, 0, v9, s[12:13]
	v_cndmask_b32_e64 v8, 0, v8, s[12:13]
	s_waitcnt vmcnt(0)
	v_pk_add_f32 v[4:5], v[4:5], v[10:11]
	v_pk_mul_f32 v[10:11], v[74:75], 0.5 op_sel_hi:[1,0]
	v_pk_add_f32 v[6:7], v[6:7], v[8:9]
	v_pk_mul_f32 v[8:9], v[66:67], 0.5 op_sel_hi:[1,0]
	v_cndmask_b32_e64 v11, 0, v11, s[12:13]
	v_cndmask_b32_e64 v10, 0, v10, s[12:13]
	v_cndmask_b32_e64 v9, 0, v9, s[12:13]
	v_cndmask_b32_e64 v8, 0, v8, s[12:13]
	v_pk_add_f32 v[0:1], v[0:1], v[10:11]
	v_pk_add_f32 v[2:3], v[2:3], v[8:9]
	v_mov_b32_e32 v10, v5
	v_mov_b32_e32 v11, v1
	v_mov_b32_e32 v8, v4
	v_mov_b32_e32 v9, v0
	v_pk_mul_f32 v[10:11], v[10:11], v[10:11]
	v_mov_b32_e32 v16, v7
	v_mov_b32_e32 v17, v3
	v_pk_fma_f32 v[8:9], v[8:9], v[8:9], v[10:11]
	v_mov_b32_e32 v10, v6
	v_mov_b32_e32 v11, v2
	v_pk_mul_f32 v[16:17], v[16:17], v[16:17]
	global_store_dwordx4 v[12:13], v[4:7], off offset:512
	global_store_dwordx4 v[12:13], v[0:3], off offset:528
	v_pk_fma_f32 v[10:11], v[10:11], v[10:11], v[16:17]
	s_nop 0
	v_pk_add_f32 v[8:9], v[8:9], v[10:11]
	s_nop 0
	v_add_f32_e32 v8, v8, v9
	v_add_f32_e32 v14, v14, v8

; __device__ __forceinline__ unsigned pk2(float lo, float hi) { unsigned r; asm volatile("v_cvt_pk_bf16_f32 %0, %1, %2" : "=v"(r) : "v"(lo), "v"(hi)); return r; }
; __device__ __forceinline__ float dot4(f32x4 v) { return (v[0] * v[0] + v[1] * v[1]) + (v[2] * v[2] + v[3] * v[3]); }
;     __device__ __forceinline__ void operator()(const f32x4 (&acc)[2][2][4][2], const Unit& u, int wr, int wc, int fr, int fq) const {
;     ...
;                 const int row = row0 + ai * HALF + m * 16; const size_t off = (size_t)row * D + col0;
;                 float q = 0.f;
; #pragma unroll
;                 for (int bj = 0; bj < 2; ++bj) {
;                     if (quad >= 0 && (quad & 1) != bj) continue;
;                     const f32x4 v0 = rr[m][bj][0] + acc[ai][bj][m][0] * scale, v1 = rr[m][bj][1] + acc[ai][bj][m][1] * scale;
;                     q += dot4(v0) + dot4(v1);
;                     __builtin_nontemporal_store(v0, (f32x4*)(out + off + bj * HALF)); __builtin_nontemporal_store(v1, (f32x4*)(out + off + bj * HALF + 4));
;                     if (An) { const f32x4 a0 = v0 * gv[bj][0], a1 = v1 * gv[bj][1]; u32x4 w; w.x = pk2(a0[0], a0[1]); w.y = pk2(a0[2], a0[3]); w.z = pk2(a1[0], a1[1]); w.w = pk2(a1[2], a1[3]);
;                         *(u32x4*)(An + off + bj * HALF) = w; }
;                 }
; __device__ __forceinline__ void ph_res_fix(int ph) {
;     ...
;                 for (int n = 0; n < 2; ++n) if (a * 2 + b == quad) acc[a][b][m][n] = s[m * 2 + n];
.LBB0_1426:
	s_cmp_eq_u32 s16, 2
	s_cselect_b64 s[10:11], -1, 0
	v_lshlrev_b64 v[98:99], 11, v[106:107]
	v_lshl_add_u64 v[110:111], v[98:99], 0, v[76:77]
	v_mov_b32_e32 v108, 0
	s_and_b64 vcc, exec, s[8:9]
	v_pk_mul_f32 v[98:99], v[94:95], 0.5 op_sel_hi:[1,0]
	v_pk_mul_f32 v[96:97], v[96:97], 0.5 op_sel_hi:[1,0]
	v_lshl_add_u64 v[94:95], v[110:111], 2, s[20:21]
	s_cbranch_vccnz .LBB0_1428
	v_pk_mul_f32 v[108:109], v[88:89], 0.5 op_sel_hi:[1,0]
	v_cndmask_b32_e64 v111, 0, v99, s[10:11]
	v_cndmask_b32_e64 v110, 0, v98, s[10:11]
	v_cndmask_b32_e64 v109, 0, v109, s[10:11]
	v_cndmask_b32_e64 v108, 0, v108, s[10:11]
	s_waitcnt vmcnt(0)
	v_pk_add_f32 v[60:61], v[60:61], v[110:111]
	v_pk_add_f32 v[62:63], v[62:63], v[108:109]
	v_pk_mul_f32 v[108:109], v[90:91], 0.5 op_sel_hi:[1,0]
	v_cndmask_b32_e64 v111, 0, v97, s[10:11]
	v_cndmask_b32_e64 v110, 0, v96, s[10:11]
	v_cndmask_b32_e64 v109, 0, v109, s[10:11]
	v_cndmask_b32_e64 v108, 0, v108, s[10:11]
	v_pk_add_f32 v[52:53], v[52:53], v[110:111]
	v_pk_add_f32 v[54:55], v[54:55], v[108:109]
	v_mov_b32_e32 v110, v61
	v_mov_b32_e32 v111, v53
	v_mov_b32_e32 v108, v60
	v_mov_b32_e32 v109, v52
	v_pk_mul_f32 v[110:111], v[110:111], v[110:111]
	v_mov_b32_e32 v112, v63
	v_mov_b32_e32 v113, v55
	v_pk_fma_f32 v[108:109], v[108:109], v[108:109], v[110:111]
	v_mov_b32_e32 v110, v62
	v_mov_b32_e32 v111, v54
	v_pk_mul_f32 v[112:113], v[112:113], v[112:113]
	global_store_dwordx4 v[94:95], v[60:63], off
	global_store_dwordx4 v[94:95], v[52:55], off offset:16
	v_pk_fma_f32 v[110:111], v[110:111], v[110:111], v[112:113]
	s_nop 0
	v_pk_add_f32 v[108:109], v[108:109], v[110:111]
	s_nop 0
	v_add_f32_e32 v108, v108, v109
.LBB0_1428:
	s_cmp_eq_u32 s16, 3
	s_cselect_b64 s[12:13], -1, 0
	s_and_b64 vcc, exec, s[6:7]
	s_cbranch_vccnz .LBB0_1430
	s_waitcnt vmcnt(1)
	v_pk_mul_f32 v[52:53], v[88:89], 0.5 op_sel_hi:[1,0]
	v_cndmask_b32_e64 v55, 0, v99, s[12:13]
	v_cndmask_b32_e64 v54, 0, v98, s[12:13]
	s_waitcnt vmcnt(0)
	v_cndmask_b32_e64 v61, 0, v53, s[12:13]
	v_cndmask_b32_e64 v60, 0, v52, s[12:13]
	v_pk_add_f32 v[52:53], v[56:57], v[54:55]
	v_pk_add_f32 v[54:55], v[58:59], v[60:61]
	v_pk_mul_f32 v[56:57], v[90:91], 0.5 op_sel_hi:[1,0]
	v_cndmask_b32_e64 v59, 0, v97, s[12:13]
	v_cndmask_b32_e64 v58, 0, v96, s[12:13]
	v_cndmask_b32_e64 v57, 0, v57, s[12:13]
	v_cndmask_b32_e64 v56, 0, v56, s[12:13]
	v_pk_add_f32 v[44:45], v[44:45], v[58:59]
	v_pk_add_f32 v[46:47], v[46:47], v[56:57]
	v_mov_b32_e32 v58, v53
	v_mov_b32_e32 v59, v45
	v_mov_b32_e32 v56, v52
	v_mov_b32_e32 v57, v44
	v_pk_mul_f32 v[58:59], v[58:59], v[58:59]
	v_mov_b32_e32 v60, v55
	v_mov_b32_e32 v61, v47
	v_pk_fma_f32 v[56:57], v[56:57], v[56:57], v[58:59]
	v_mov_b32_e32 v58, v54
	v_mov_b32_e32 v59, v46
	v_pk_mul_f32 v[60:61], v[60:61], v[60:61]
	global_store_dwordx4 v[94:95], v[52:55], off offset:512
	global_store_dwordx4 v[94:95], v[44:47], off offset:528
	v_pk_fma_f32 v[58:59], v[58:59], v[58:59], v[60:61]
	s_nop 0
	v_pk_add_f32 v[56:57], v[56:57], v[58:59]
	s_nop 0
	v_add_f32_e32 v56, v56, v57
	v_add_f32_e32 v108, v108, v56

; __device__ __forceinline__ unsigned pk2(float lo, float hi) { unsigned r; asm volatile("v_cvt_pk_bf16_f32 %0, %1, %2" : "=v"(r) : "v"(lo), "v"(hi)); return r; }
; __device__ __forceinline__ float dot4(f32x4 v) { return (v[0] * v[0] + v[1] * v[1]) + (v[2] * v[2] + v[3] * v[3]); }
;     __device__ __forceinline__ void operator()(const f32x4 (&acc)[2][2][4][2], const Unit& u, int wr, int wc, int fr, int fq) const {
;     ...
;                 const int row = row0 + ai * HALF + m * 16; const size_t off = (size_t)row * D + col0;
;                 float q = 0.f;
; #pragma unroll
;                 for (int bj = 0; bj < 2; ++bj) {
;                     if (quad >= 0 && (quad & 1) != bj) continue;
;                     const f32x4 v0 = rr[m][bj][0] + acc[ai][bj][m][0] * scale, v1 = rr[m][bj][1] + acc[ai][bj][m][1] * scale;
;                     q += dot4(v0) + dot4(v1);
;                     __builtin_nontemporal_store(v0, (f32x4*)(out + off + bj * HALF)); __builtin_nontemporal_store(v1, (f32x4*)(out + off + bj * HALF + 4));
;                     if (An) { const f32x4 a0 = v0 * gv[bj][0], a1 = v1 * gv[bj][1]; u32x4 w; w.x = pk2(a0[0], a0[1]); w.y = pk2(a0[2], a0[3]); w.z = pk2(a1[0], a1[1]); w.w = pk2(a1[2], a1[3]);
;                         *(u32x4*)(An + off + bj * HALF) = w; }
;                 }
; __device__ __forceinline__ void ph_res_fix(int ph) {
;     ...
;                 for (int n = 0; n < 2; ++n) if (a * 2 + b == quad) acc[a][b][m][n] = s[m * 2 + n];
.LBB0_1432:
	s_or_b64 exec, exec, s[14:15]
	s_waitcnt lgkmcnt(0)
	v_lshlrev_b64 v[44:45], 11, v[104:105]
	v_lshl_add_u64 v[44:45], v[44:45], 0, v[76:77]
	s_waitcnt vmcnt(0)
	v_mov_b32_e32 v56, 0
	s_and_b64 vcc, exec, s[8:9]
	v_pk_mul_f32 v[52:53], v[86:87], 0.5 op_sel_hi:[1,0]
	v_pk_mul_f32 v[46:47], v[92:93], 0.5 op_sel_hi:[1,0]
	v_lshl_add_u64 v[44:45], v[44:45], 2, s[20:21]
	s_cbranch_vccnz .LBB0_1434
	v_pk_mul_f32 v[56:57], v[78:79], 0.5 op_sel_hi:[1,0]
	v_cndmask_b32_e64 v59, 0, v53, s[10:11]
	v_cndmask_b32_e64 v58, 0, v52, s[10:11]
	v_cndmask_b32_e64 v57, 0, v57, s[10:11]
	v_cndmask_b32_e64 v56, 0, v56, s[10:11]
	v_pk_add_f32 v[48:49], v[48:49], v[58:59]
	v_pk_add_f32 v[50:51], v[50:51], v[56:57]
	v_pk_mul_f32 v[56:57], v[82:83], 0.5 op_sel_hi:[1,0]
	v_cndmask_b32_e64 v59, 0, v47, s[10:11]
	v_cndmask_b32_e64 v58, 0, v46, s[10:11]
	v_cndmask_b32_e64 v57, 0, v57, s[10:11]
	v_cndmask_b32_e64 v56, 0, v56, s[10:11]
	v_pk_add_f32 v[40:41], v[40:41], v[58:59]
	v_pk_add_f32 v[42:43], v[42:43], v[56:57]
	v_mov_b32_e32 v58, v49
	v_mov_b32_e32 v59, v41
	v_mov_b32_e32 v56, v48
	v_mov_b32_e32 v57, v40
	v_pk_mul_f32 v[58:59], v[58:59], v[58:59]
	v_mov_b32_e32 v60, v51
	v_mov_b32_e32 v61, v43
	v_pk_fma_f32 v[56:57], v[56:57], v[56:57], v[58:59]
	v_mov_b32_e32 v58, v50
	v_mov_b32_e32 v59, v42
	v_pk_mul_f32 v[60:61], v[60:61], v[60:61]
	global_store_dwordx4 v[44:45], v[48:51], off
	global_store_dwordx4 v[44:45], v[40:43], off offset:16
	v_pk_fma_f32 v[58:59], v[58:59], v[58:59], v[60:61]
	s_nop 0
	v_pk_add_f32 v[56:57], v[56:57], v[58:59]
	s_nop 0
	v_add_f32_e32 v56, v56, v57
.LBB0_1434:
	s_and_b64 vcc, exec, s[6:7]
	s_cbranch_vccnz .LBB0_1436
	v_pk_mul_f32 v[40:41], v[78:79], 0.5 op_sel_hi:[1,0]
	v_cndmask_b32_e64 v43, 0, v53, s[12:13]
	v_cndmask_b32_e64 v42, 0, v52, s[12:13]
	v_cndmask_b32_e64 v41, 0, v41, s[12:13]
	v_cndmask_b32_e64 v40, 0, v40, s[12:13]
	v_pk_add_f32 v[36:37], v[36:37], v[42:43]
	v_pk_add_f32 v[38:39], v[38:39], v[40:41]
	v_pk_mul_f32 v[40:41], v[82:83], 0.5 op_sel_hi:[1,0]
	v_cndmask_b32_e64 v43, 0, v47, s[12:13]
	v_cndmask_b32_e64 v42, 0, v46, s[12:13]
	v_cndmask_b32_e64 v41, 0, v41, s[12:13]
	v_cndmask_b32_e64 v40, 0, v40, s[12:13]
	v_pk_add_f32 v[28:29], v[28:29], v[42:43]
	v_pk_add_f32 v[30:31], v[30:31], v[40:41]
	v_mov_b32_e32 v42, v37
	v_mov_b32_e32 v43, v29
	v_mov_b32_e32 v40, v36
	v_mov_b32_e32 v41, v28
	v_pk_mul_f32 v[42:43], v[42:43], v[42:43]
	v_mov_b32_e32 v46, v39
	v_mov_b32_e32 v47, v31
	v_pk_fma_f32 v[40:41], v[40:41], v[40:41], v[42:43]
	v_mov_b32_e32 v42, v38
	v_mov_b32_e32 v43, v30
	v_pk_mul_f32 v[46:47], v[46:47], v[46:47]
	global_store_dwordx4 v[44:45], v[36:39], off offset:512
	global_store_dwordx4 v[44:45], v[28:31], off offset:528
	v_pk_fma_f32 v[42:43], v[42:43], v[42:43], v[46:47]
	s_nop 0
	v_pk_add_f32 v[40:41], v[40:41], v[42:43]
	s_nop 0
	v_add_f32_e32 v40, v40, v41
	v_add_f32_e32 v56, v56, v40

; __device__ __forceinline__ unsigned pk2(float lo, float hi) { unsigned r; asm volatile("v_cvt_pk_bf16_f32 %0, %1, %2" : "=v"(r) : "v"(lo), "v"(hi)); return r; }
; __device__ __forceinline__ float dot4(f32x4 v) { return (v[0] * v[0] + v[1] * v[1]) + (v[2] * v[2] + v[3] * v[3]); }
;     __device__ __forceinline__ void operator()(const f32x4 (&acc)[2][2][4][2], const Unit& u, int wr, int wc, int fr, int fq) const {
;     ...
;                 const int row = row0 + ai * HALF + m * 16; const size_t off = (size_t)row * D + col0;
;                 float q = 0.f;
; #pragma unroll
;                 for (int bj = 0; bj < 2; ++bj) {
;                     if (quad >= 0 && (quad & 1) != bj) continue;
;                     const f32x4 v0 = rr[m][bj][0] + acc[ai][bj][m][0] * scale, v1 = rr[m][bj][1] + acc[ai][bj][m][1] * scale;
;                     q += dot4(v0) + dot4(v1);
;                     __builtin_nontemporal_store(v0, (f32x4*)(out + off + bj * HALF)); __builtin_nontemporal_store(v1, (f32x4*)(out + off + bj * HALF + 4));
;                     if (An) { const f32x4 a0 = v0 * gv[bj][0], a1 = v1 * gv[bj][1]; u32x4 w; w.x = pk2(a0[0], a0[1]); w.y = pk2(a0[2], a0[3]); w.z = pk2(a1[0], a1[1]); w.w = pk2(a1[2], a1[3]);
;                         *(u32x4*)(An + off + bj * HALF) = w; }
;                 }
; __device__ __forceinline__ void ph_res_fix(int ph) {
;     ...
;                 for (int n = 0; n < 2; ++n) if (a * 2 + b == quad) acc[a][b][m][n] = s[m * 2 + n];
.LBB0_1438:
	s_or_b64 exec, exec, s[14:15]
	s_waitcnt lgkmcnt(0)
	v_lshlrev_b64 v[28:29], 11, v[102:103]
	v_lshl_add_u64 v[28:29], v[28:29], 0, v[76:77]
	v_mov_b32_e32 v38, 0
	s_and_b64 vcc, exec, s[8:9]
	v_pk_mul_f32 v[36:37], v[80:81], 0.5 op_sel_hi:[1,0]
	v_pk_mul_f32 v[30:31], v[84:85], 0.5 op_sel_hi:[1,0]
	v_lshl_add_u64 v[28:29], v[28:29], 2, s[20:21]
	s_cbranch_vccnz .LBB0_1440
	v_pk_mul_f32 v[38:39], v[68:69], 0.5 op_sel_hi:[1,0]
	v_cndmask_b32_e64 v41, 0, v37, s[10:11]
	v_cndmask_b32_e64 v40, 0, v36, s[10:11]
	v_cndmask_b32_e64 v39, 0, v39, s[10:11]
	v_cndmask_b32_e64 v38, 0, v38, s[10:11]
	v_pk_add_f32 v[32:33], v[32:33], v[40:41]
	v_pk_add_f32 v[34:35], v[34:35], v[38:39]
	v_pk_mul_f32 v[38:39], v[72:73], 0.5 op_sel_hi:[1,0]
	v_cndmask_b32_e64 v41, 0, v31, s[10:11]
	v_cndmask_b32_e64 v40, 0, v30, s[10:11]
	v_cndmask_b32_e64 v39, 0, v39, s[10:11]
	v_cndmask_b32_e64 v38, 0, v38, s[10:11]
	v_pk_add_f32 v[24:25], v[24:25], v[40:41]
	v_pk_add_f32 v[26:27], v[26:27], v[38:39]
	v_mov_b32_e32 v40, v33
	v_mov_b32_e32 v41, v25
	v_mov_b32_e32 v38, v32
	v_mov_b32_e32 v39, v24
	v_pk_mul_f32 v[40:41], v[40:41], v[40:41]
	v_mov_b32_e32 v42, v35
	v_mov_b32_e32 v43, v27
	v_pk_fma_f32 v[38:39], v[38:39], v[38:39], v[40:41]
	v_mov_b32_e32 v40, v34
	v_mov_b32_e32 v41, v26
	v_pk_mul_f32 v[42:43], v[42:43], v[42:43]
	global_store_dwordx4 v[28:29], v[32:35], off
	global_store_dwordx4 v[28:29], v[24:27], off offset:16
	v_pk_fma_f32 v[40:41], v[40:41], v[40:41], v[42:43]
	s_nop 0
	v_pk_add_f32 v[38:39], v[38:39], v[40:41]
	s_nop 0
	v_add_f32_e32 v38, v38, v39
.LBB0_1440:
	s_and_b64 vcc, exec, s[6:7]
	s_cbranch_vccnz .LBB0_1442
	v_pk_mul_f32 v[24:25], v[68:69], 0.5 op_sel_hi:[1,0]
	v_cndmask_b32_e64 v27, 0, v37, s[12:13]
	v_cndmask_b32_e64 v26, 0, v36, s[12:13]
	v_cndmask_b32_e64 v25, 0, v25, s[12:13]
	v_cndmask_b32_e64 v24, 0, v24, s[12:13]
	v_pk_add_f32 v[20:21], v[20:21], v[26:27]
	v_pk_add_f32 v[22:23], v[22:23], v[24:25]
	v_pk_mul_f32 v[24:25], v[72:73], 0.5 op_sel_hi:[1,0]
	v_cndmask_b32_e64 v27, 0, v31, s[12:13]
	v_cndmask_b32_e64 v26, 0, v30, s[12:13]
	v_cndmask_b32_e64 v25, 0, v25, s[12:13]
	v_cndmask_b32_e64 v24, 0, v24, s[12:13]
	v_pk_add_f32 v[12:13], v[12:13], v[26:27]
	v_pk_add_f32 v[14:15], v[14:15], v[24:25]
	v_mov_b32_e32 v26, v21
	v_mov_b32_e32 v27, v13
	v_mov_b32_e32 v24, v20
	v_mov_b32_e32 v25, v12
	v_pk_mul_f32 v[26:27], v[26:27], v[26:27]
	v_mov_b32_e32 v30, v23
	v_mov_b32_e32 v31, v15
	v_pk_fma_f32 v[24:25], v[24:25], v[24:25], v[26:27]
	v_mov_b32_e32 v26, v22
	v_mov_b32_e32 v27, v14
	v_pk_mul_f32 v[30:31], v[30:31], v[30:31]
	global_store_dwordx4 v[28:29], v[20:23], off offset:512
	global_store_dwordx4 v[28:29], v[12:15], off offset:528
	v_pk_fma_f32 v[26:27], v[26:27], v[26:27], v[30:31]
	s_nop 0
	v_pk_add_f32 v[24:25], v[24:25], v[26:27]
	s_nop 0
	v_add_f32_e32 v24, v24, v25
	v_add_f32_e32 v38, v38, v24

; __device__ __forceinline__ unsigned pk2(float lo, float hi) { unsigned r; asm volatile("v_cvt_pk_bf16_f32 %0, %1, %2" : "=v"(r) : "v"(lo), "v"(hi)); return r; }
; __device__ __forceinline__ float dot4(f32x4 v) { return (v[0] * v[0] + v[1] * v[1]) + (v[2] * v[2] + v[3] * v[3]); }
;     __device__ __forceinline__ void operator()(const f32x4 (&acc)[2][2][4][2], const Unit& u, int wr, int wc, int fr, int fq) const {
;     ...
;                 const int row = row0 + ai * HALF + m * 16; const size_t off = (size_t)row * D + col0;
;                 float q = 0.f;
; #pragma unroll
;                 for (int bj = 0; bj < 2; ++bj) {
;                     if (quad >= 0 && (quad & 1) != bj) continue;
;                     const f32x4 v0 = rr[m][bj][0] + acc[ai][bj][m][0] * scale, v1 = rr[m][bj][1] + acc[ai][bj][m][1] * scale;
;                     q += dot4(v0) + dot4(v1);
;                     __builtin_nontemporal_store(v0, (f32x4*)(out + off + bj * HALF)); __builtin_nontemporal_store(v1, (f32x4*)(out + off + bj * HALF + 4));
;                     if (An) { const f32x4 a0 = v0 * gv[bj][0], a1 = v1 * gv[bj][1]; u32x4 w; w.x = pk2(a0[0], a0[1]); w.y = pk2(a0[2], a0[3]); w.z = pk2(a1[0], a1[1]); w.w = pk2(a1[2], a1[3]);
;                         *(u32x4*)(An + off + bj * HALF) = w; }
;                 }
; __device__ __forceinline__ void ph_res_fix(int ph) {
;     ...
;                 for (int n = 0; n < 2; ++n) if (a * 2 + b == quad) acc[a][b][m][n] = s[m * 2 + n];
.LBB0_1444:
	s_or_b64 exec, exec, s[14:15]
	s_waitcnt lgkmcnt(0)
	v_lshlrev_b64 v[12:13], 11, v[100:101]
	v_lshl_add_u64 v[12:13], v[12:13], 0, v[76:77]
	v_mov_b32_e32 v22, 0
	s_and_b64 vcc, exec, s[8:9]
	v_pk_mul_f32 v[20:21], v[70:71], 0.5 op_sel_hi:[1,0]
	v_pk_mul_f32 v[14:15], v[74:75], 0.5 op_sel_hi:[1,0]
	v_lshl_add_u64 v[12:13], v[12:13], 2, s[20:21]
	s_cbranch_vccnz .LBB0_1446
	v_pk_mul_f32 v[22:23], v[64:65], 0.5 op_sel_hi:[1,0]
	v_cndmask_b32_e64 v25, 0, v21, s[10:11]
	v_cndmask_b32_e64 v24, 0, v20, s[10:11]
	v_cndmask_b32_e64 v23, 0, v23, s[10:11]
	v_cndmask_b32_e64 v22, 0, v22, s[10:11]
	v_pk_add_f32 v[16:17], v[16:17], v[24:25]
	v_pk_add_f32 v[18:19], v[18:19], v[22:23]
	v_pk_mul_f32 v[22:23], v[66:67], 0.5 op_sel_hi:[1,0]
	v_cndmask_b32_e64 v25, 0, v15, s[10:11]
	v_cndmask_b32_e64 v24, 0, v14, s[10:11]
	v_cndmask_b32_e64 v23, 0, v23, s[10:11]
	v_cndmask_b32_e64 v22, 0, v22, s[10:11]
	v_pk_add_f32 v[8:9], v[8:9], v[24:25]
	v_pk_add_f32 v[10:11], v[10:11], v[22:23]
	v_mov_b32_e32 v24, v17
	v_mov_b32_e32 v25, v9
	v_mov_b32_e32 v22, v16
	v_mov_b32_e32 v23, v8
	v_pk_mul_f32 v[24:25], v[24:25], v[24:25]
	v_mov_b32_e32 v26, v19
	v_mov_b32_e32 v27, v11
	v_pk_fma_f32 v[22:23], v[22:23], v[22:23], v[24:25]
	v_mov_b32_e32 v24, v18
	v_mov_b32_e32 v25, v10
	v_pk_mul_f32 v[26:27], v[26:27], v[26:27]
	global_store_dwordx4 v[12:13], v[16:19], off
	global_store_dwordx4 v[12:13], v[8:11], off offset:16
	v_pk_fma_f32 v[24:25], v[24:25], v[24:25], v[26:27]
	s_nop 0
	v_pk_add_f32 v[22:23], v[22:23], v[24:25]
	s_nop 0
	v_add_f32_e32 v22, v22, v23
.LBB0_1446:
	s_and_b64 vcc, exec, s[6:7]
	s_cbranch_vccnz .LBB0_1448
	v_pk_mul_f32 v[8:9], v[64:65], 0.5 op_sel_hi:[1,0]
	v_cndmask_b32_e64 v11, 0, v21, s[12:13]
	v_cndmask_b32_e64 v10, 0, v20, s[12:13]
	v_cndmask_b32_e64 v9, 0, v9, s[12:13]
	v_cndmask_b32_e64 v8, 0, v8, s[12:13]
	v_pk_add_f32 v[4:5], v[4:5], v[10:11]
	v_pk_add_f32 v[6:7], v[6:7], v[8:9]
	v_pk_mul_f32 v[8:9], v[66:67], 0.5 op_sel_hi:[1,0]
	v_cndmask_b32_e64 v11, 0, v15, s[12:13]
	v_cndmask_b32_e64 v10, 0, v14, s[12:13]
	v_cndmask_b32_e64 v9, 0, v9, s[12:13]
	v_cndmask_b32_e64 v8, 0, v8, s[12:13]
	v_pk_add_f32 v[0:1], v[0:1], v[10:11]
	v_pk_add_f32 v[2:3], v[2:3], v[8:9]
	v_mov_b32_e32 v10, v5
	v_mov_b32_e32 v11, v1
	v_mov_b32_e32 v8, v4
	v_mov_b32_e32 v9, v0
	v_pk_mul_f32 v[10:11], v[10:11], v[10:11]
	v_mov_b32_e32 v14, v7
	v_mov_b32_e32 v15, v3
	v_pk_fma_f32 v[8:9], v[8:9], v[8:9], v[10:11]
	v_mov_b32_e32 v10, v6
	v_mov_b32_e32 v11, v2
	v_pk_mul_f32 v[14:15], v[14:15], v[14:15]
	global_store_dwordx4 v[12:13], v[4:7], off offset:512
	global_store_dwordx4 v[12:13], v[0:3], off offset:528
	v_pk_fma_f32 v[10:11], v[10:11], v[10:11], v[14:15]
	s_nop 0
	v_pk_add_f32 v[8:9], v[8:9], v[10:11]
	s_nop 0
	v_add_f32_e32 v8, v8, v9
	v_add_f32_e32 v22, v22, v8
